# GEMM: vmcnt wait selection without taken branches before each k-step barrier; work-queue atomic prefetched at epilogue start; NA rpb loads hoisted
# speedup vs baseline: 1.0840x; 1.0100x over previous
.LBB0_108:
	s_getreg_b32 s0, hwreg(HW_REG_XCC_ID, 0, 4)
	s_lshl_b32 s40, s11, 3
	s_and_b32 s10, s0, 7
	v_writelane_b32 v254, s11, 49
	s_mov_b32 s0, s40
	s_ashr_i32 s41, s40, 31
	v_writelane_b32 v254, s0, 50
	v_mov_b32_e32 v16, s10
	v_mov_b32_e32 v199, v17
	v_writelane_b32 v254, s1, 51
	s_lshl_b64 s[0:1], s[40:41], 2
	v_readlane_b32 s40, v252, 55
	v_readlane_b32 s41, v252, 56
	s_add_u32 s0, s40, s0
	s_addc_u32 s1, s41, s1
	s_mov_b32 s99, 0
	s_branch .LBB0_110

.LBB0_114:
	v_cmp_gt_i32_e32 vcc, 8, v199
	s_or_b64 s[42:43], s[42:43], exec
	s_and_saveexec_b64 s[44:45], vcc
	s_cbranch_execz .LBB0_113
	s_cmp_eq_u32 s99, 1
	s_cbranch_scc0 .Lpf_none_ip
	s_mov_b32 s99, 0
	s_waitcnt vmcnt(0)
	v_mov_b32_e32 v0, v248
	s_branch .Lpf_have_ip
.Lpf_none_ip:
	v_lshl_add_u64 v[2:3], v[16:17], 2, s[0:1]
	global_atomic_add v0, v[2:3], v229, off sc0
.Lpf_have_ip:
	s_movk_i32 s25, 0xd7
	s_waitcnt vmcnt(0)
	v_cmp_lt_i32_e32 vcc, s25, v0
	s_and_saveexec_b64 s[48:49], vcc
	s_xor_b64 s[48:49], exec, s[48:49]
	s_cbranch_execz .LBB0_121
	s_movk_i32 s25, 0xe9
	v_cmp_lt_u32_e32 vcc, s25, v0
	s_and_saveexec_b64 s[46:47], vcc
	s_xor_b64 s[46:47], exec, s[46:47]
	v_add_u32_e32 v0, 1, v16
	v_and_b32_e32 v16, 7, v0
	v_add_u32_e32 v199, 1, v199
	s_or_saveexec_b64 s[50:51], s[46:47]
	s_mov_b64 s[46:47], -1
	s_xor_b64 exec, exec, s[50:51]
	v_mad_u64_u32 v[0:1], s[46:47], v16, 18, v[0:1]
	v_mov_b32_e32 v1, 0xffffca3f
	v_lshl_add_u32 v1, v0, 6, v1
	s_xor_b64 s[46:47], exec, -1
	s_or_b64 exec, exec, s[50:51]

.LBB0_128:
	s_lshl_b32 s40, s42, 15
	v_mfma_f32_16x16x32_bf16 v[158:161], v[0:3], v[58:61], v[158:161]
	v_add_u32_e32 v162, s40, v240
	s_mov_b64 s[10:11], -1
	s_cmp_gt_u32 s45, 28
	v_mfma_f32_16x16x32_bf16 v[154:157], v[4:7], v[58:61], v[154:157]
	v_mfma_f32_16x16x32_bf16 v[150:153], v[8:11], v[58:61], v[150:153]
	v_mfma_f32_16x16x32_bf16 v[146:149], v[12:15], v[58:61], v[146:149]
	ds_read_b128 v[58:61], v162 offset:4096
	v_mfma_f32_16x16x32_bf16 v[142:145], v[0:3], v[54:57], v[142:145]
	v_mfma_f32_16x16x32_bf16 v[138:141], v[4:7], v[54:57], v[138:141]
	v_mfma_f32_16x16x32_bf16 v[134:137], v[8:11], v[54:57], v[134:137]
	v_mfma_f32_16x16x32_bf16 v[130:133], v[12:15], v[54:57], v[130:133]
	ds_read_b128 v[54:57], v162 offset:5120
	v_mfma_f32_16x16x32_bf16 v[126:129], v[0:3], v[50:53], v[126:129]
	v_mfma_f32_16x16x32_bf16 v[122:125], v[4:7], v[50:53], v[122:125]
	v_mfma_f32_16x16x32_bf16 v[118:121], v[8:11], v[50:53], v[118:121]
	v_mfma_f32_16x16x32_bf16 v[114:117], v[12:15], v[50:53], v[114:117]
	ds_read_b128 v[50:53], v162 offset:6144
	ds_read_b128 v[174:177], v162 offset:7168
	v_mfma_f32_16x16x32_bf16 v[110:113], v[0:3], v[38:41], v[110:113]
	s_waitcnt lgkmcnt(0)
	v_mfma_f32_16x16x32_bf16 v[106:109], v[4:7], v[38:41], v[106:109]
	v_mfma_f32_16x16x32_bf16 v[102:105], v[8:11], v[38:41], v[102:105]
	v_mfma_f32_16x16x32_bf16 v[86:89], v[12:15], v[38:41], v[86:89]
	s_cbranch_scc1 .Lvw_ipa
	s_waitcnt vmcnt(8)

.Ldma_ipa_3:
	v_mfma_f32_16x16x32_bf16 v[46:49], v[8:11], v[54:57], v[46:49]
	v_mfma_f32_16x16x32_bf16 v[42:45], v[12:15], v[54:57], v[42:45]
	ds_read_b128 v[54:57], v202 offset:1024
	v_mfma_f32_16x16x32_bf16 v[34:37], v[0:3], v[50:53], v[34:37]
	v_mfma_f32_16x16x32_bf16 v[30:33], v[4:7], v[50:53], v[30:33]
	v_mfma_f32_16x16x32_bf16 v[26:29], v[8:11], v[50:53], v[26:29]
	v_mfma_f32_16x16x32_bf16 v[22:25], v[12:15], v[50:53], v[22:25]
	ds_read_b128 v[50:53], v202 offset:2048
	ds_read_b128 v[38:41], v202 offset:3072
	s_nop 0
	ds_read_b128 v[190:193], v202 offset:4096
	ds_read_b128 v[186:189], v202 offset:5120
	ds_read_b128 v[182:185], v202 offset:6144
	v_mfma_f32_16x16x32_bf16 v[18:21], v[0:3], v[174:177], v[18:21]
	v_mfma_f32_16x16x32_bf16 v[98:101], v[4:7], v[174:177], v[98:101]
	v_mfma_f32_16x16x32_bf16 v[90:93], v[8:11], v[174:177], v[90:93]
	v_mfma_f32_16x16x32_bf16 v[74:77], v[12:15], v[174:177], v[74:77]
	ds_read_b128 v[174:177], v202 offset:7168
	s_nop 0
	s_waitcnt lgkmcnt(4)
	v_mfma_f32_16x16x32_bf16 v[158:161], v[178:181], v[58:61], v[158:161]
	v_mfma_f32_16x16x32_bf16 v[154:157], v[170:173], v[58:61], v[154:157]
	v_mfma_f32_16x16x32_bf16 v[150:153], v[166:169], v[58:61], v[150:153]
	v_mfma_f32_16x16x32_bf16 v[146:149], v[162:165], v[58:61], v[146:149]
	v_mfma_f32_16x16x32_bf16 v[142:145], v[178:181], v[54:57], v[142:145]
	v_mfma_f32_16x16x32_bf16 v[138:141], v[170:173], v[54:57], v[138:141]
	v_mfma_f32_16x16x32_bf16 v[134:137], v[166:169], v[54:57], v[134:137]
	v_mfma_f32_16x16x32_bf16 v[130:133], v[162:165], v[54:57], v[130:133]
	v_mfma_f32_16x16x32_bf16 v[126:129], v[178:181], v[50:53], v[126:129]
	v_mfma_f32_16x16x32_bf16 v[122:125], v[170:173], v[50:53], v[122:125]
	v_mfma_f32_16x16x32_bf16 v[118:121], v[166:169], v[50:53], v[118:121]
	v_mfma_f32_16x16x32_bf16 v[114:117], v[162:165], v[50:53], v[114:117]
	v_mfma_f32_16x16x32_bf16 v[110:113], v[178:181], v[38:41], v[110:113]
	v_mfma_f32_16x16x32_bf16 v[106:109], v[170:173], v[38:41], v[106:109]
	v_mfma_f32_16x16x32_bf16 v[102:105], v[166:169], v[38:41], v[102:105]
	v_mfma_f32_16x16x32_bf16 v[86:89], v[162:165], v[38:41], v[86:89]
	s_cbranch_vccnz .LBB0_143
	s_cmp_lt_u32 s44, 2
	s_cbranch_scc1 .Lvw_ipb
	s_waitcnt vmcnt(8)

.Lvw_ipa:
	s_waitcnt vmcnt(0)
	s_branch .LBB0_132
.Lvw_ipb:
	s_cmp_lg_u32 s44, 1
	s_cbranch_scc0 .Lvw_ipb4
	s_waitcnt vmcnt(0)
	s_branch .LBB0_143
.Lvw_ipb4:
	s_waitcnt vmcnt(4)
	s_branch .LBB0_143

.LBB0_148:
	v_readfirstlane_b32 s99, v195
	s_mov_b64 s[100:101], exec
	s_cmp_lg_u32 s99, 0
	s_cbranch_scc1 .Lpfa_skip_ip
	s_mov_b64 exec, 1
	v_lshl_add_u64 v[248:249], v[16:17], 2, s[0:1]
	global_atomic_add v248, v[248:249], v229, off sc0
	s_mov_b64 exec, s[100:101]
.Lpfa_skip_ip:
	s_mov_b32 s99, 1
	v_or_b32_e32 v1, s25, v238
	v_and_b32_e32 v0, 0xc0, v203
	v_add_u32_e32 v8, v1, v239
	v_lshlrev_b32_e32 v1, 2, v201
	v_or3_b32 v6, v1, v0, s34
	v_mov_b64_e32 v[0:1], s[30:31]
	v_mad_i64_i32 v[2:3], s[10:11], v8, s33, v[0:1]
	v_lshlrev_b32_e32 v6, 1, v6
	v_mov_b32_e32 v7, v17
	v_cvt_pk_bf16_f32 v4, v158, v159
	v_cvt_pk_bf16_f32 v5, v160, v161
	v_lshl_add_u64 v[2:3], v[2:3], 0, v[6:7]
	global_store_dwordx2 v[2:3], v[4:5], off
	v_cvt_pk_bf16_f32 v4, v154, v155
	v_cvt_pk_bf16_f32 v5, v156, v157
	global_store_dwordx2 v[2:3], v[4:5], off offset:32
	v_cvt_pk_bf16_f32 v4, v150, v151
	v_cvt_pk_bf16_f32 v5, v152, v153
	global_store_dwordx2 v[2:3], v[4:5], off offset:64
	v_cvt_pk_bf16_f32 v4, v146, v147
	v_cvt_pk_bf16_f32 v5, v148, v149
	global_store_dwordx2 v[2:3], v[4:5], off offset:96
	v_or_b32_e32 v2, 16, v8
	v_mad_i64_i32 v[2:3], s[10:11], v2, s33, v[0:1]
	v_cvt_pk_bf16_f32 v4, v142, v143
	v_cvt_pk_bf16_f32 v5, v144, v145
	v_lshl_add_u64 v[2:3], v[2:3], 0, v[6:7]
	global_store_dwordx2 v[2:3], v[4:5], off
	v_cvt_pk_bf16_f32 v4, v138, v139
	v_cvt_pk_bf16_f32 v5, v140, v141
	global_store_dwordx2 v[2:3], v[4:5], off offset:32
	v_cvt_pk_bf16_f32 v4, v134, v135
	v_cvt_pk_bf16_f32 v5, v136, v137
	global_store_dwordx2 v[2:3], v[4:5], off offset:64
	v_cvt_pk_bf16_f32 v4, v130, v131
	v_cvt_pk_bf16_f32 v5, v132, v133
	global_store_dwordx2 v[2:3], v[4:5], off offset:96
	v_or_b32_e32 v2, 32, v8
	v_mad_i64_i32 v[2:3], s[10:11], v2, s33, v[0:1]
	v_cvt_pk_bf16_f32 v4, v126, v127
	v_cvt_pk_bf16_f32 v5, v128, v129
	v_lshl_add_u64 v[2:3], v[2:3], 0, v[6:7]
	global_store_dwordx2 v[2:3], v[4:5], off
	v_cvt_pk_bf16_f32 v4, v122, v123
	v_cvt_pk_bf16_f32 v5, v124, v125
	global_store_dwordx2 v[2:3], v[4:5], off offset:32
	v_cvt_pk_bf16_f32 v4, v118, v119
	v_cvt_pk_bf16_f32 v5, v120, v121
	global_store_dwordx2 v[2:3], v[4:5], off offset:64
	v_cvt_pk_bf16_f32 v4, v114, v115
	v_cvt_pk_bf16_f32 v5, v116, v117
	global_store_dwordx2 v[2:3], v[4:5], off offset:96
	v_or_b32_e32 v2, 48, v8
	v_mad_i64_i32 v[2:3], s[10:11], v2, s33, v[0:1]
	v_cvt_pk_bf16_f32 v4, v110, v111
	v_cvt_pk_bf16_f32 v5, v112, v113
	v_lshl_add_u64 v[2:3], v[2:3], 0, v[6:7]
	global_store_dwordx2 v[2:3], v[4:5], off
	v_cvt_pk_bf16_f32 v4, v106, v107
	v_cvt_pk_bf16_f32 v5, v108, v109
	global_store_dwordx2 v[2:3], v[4:5], off offset:32
	v_cvt_pk_bf16_f32 v4, v102, v103
	v_cvt_pk_bf16_f32 v5, v104, v105
	global_store_dwordx2 v[2:3], v[4:5], off offset:64
	v_cvt_pk_bf16_f32 v4, v86, v87
	v_cvt_pk_bf16_f32 v5, v88, v89
	global_store_dwordx2 v[2:3], v[4:5], off offset:96
	v_or_b32_e32 v2, 64, v8
	v_mad_i64_i32 v[2:3], s[10:11], v2, s33, v[0:1]
	v_cvt_pk_bf16_f32 v4, v94, v95
	v_cvt_pk_bf16_f32 v5, v96, v97
	v_lshl_add_u64 v[2:3], v[2:3], 0, v[6:7]
	global_store_dwordx2 v[2:3], v[4:5], off
	v_cvt_pk_bf16_f32 v4, v82, v83
	v_cvt_pk_bf16_f32 v5, v84, v85
	global_store_dwordx2 v[2:3], v[4:5], off offset:32
	v_cvt_pk_bf16_f32 v4, v78, v79
	v_cvt_pk_bf16_f32 v5, v80, v81
	global_store_dwordx2 v[2:3], v[4:5], off offset:64
	v_cvt_pk_bf16_f32 v4, v70, v71
	v_cvt_pk_bf16_f32 v5, v72, v73
	global_store_dwordx2 v[2:3], v[4:5], off offset:96
	v_or_b32_e32 v2, 0x50, v8
	v_mad_i64_i32 v[2:3], s[10:11], v2, s33, v[0:1]
	v_cvt_pk_bf16_f32 v4, v66, v67
	v_cvt_pk_bf16_f32 v5, v68, v69
	v_lshl_add_u64 v[2:3], v[2:3], 0, v[6:7]
	global_store_dwordx2 v[2:3], v[4:5], off
	v_cvt_pk_bf16_f32 v4, v62, v63
	v_cvt_pk_bf16_f32 v5, v64, v65
	global_store_dwordx2 v[2:3], v[4:5], off offset:32
	v_cvt_pk_bf16_f32 v4, v46, v47
	v_cvt_pk_bf16_f32 v5, v48, v49
	global_store_dwordx2 v[2:3], v[4:5], off offset:64
	v_cvt_pk_bf16_f32 v4, v42, v43
	v_cvt_pk_bf16_f32 v5, v44, v45
	global_store_dwordx2 v[2:3], v[4:5], off offset:96
	v_or_b32_e32 v2, 0x60, v8
	v_mad_i64_i32 v[2:3], s[10:11], v2, s33, v[0:1]
	v_cvt_pk_bf16_f32 v4, v34, v35
	v_cvt_pk_bf16_f32 v5, v36, v37
	v_lshl_add_u64 v[2:3], v[2:3], 0, v[6:7]
	global_store_dwordx2 v[2:3], v[4:5], off
	v_cvt_pk_bf16_f32 v4, v30, v31
	v_cvt_pk_bf16_f32 v5, v32, v33
	global_store_dwordx2 v[2:3], v[4:5], off offset:32
	v_cvt_pk_bf16_f32 v4, v26, v27
	v_cvt_pk_bf16_f32 v5, v28, v29
	global_store_dwordx2 v[2:3], v[4:5], off offset:64
	v_cvt_pk_bf16_f32 v4, v22, v23
	v_cvt_pk_bf16_f32 v5, v24, v25
	global_store_dwordx2 v[2:3], v[4:5], off offset:96
	v_or_b32_e32 v2, 0x70, v8
	v_mad_i64_i32 v[0:1], s[10:11], v2, s33, v[0:1]
	v_cvt_pk_bf16_f32 v2, v18, v19
	v_cvt_pk_bf16_f32 v3, v20, v21
	v_lshl_add_u64 v[0:1], v[0:1], 0, v[6:7]
	global_store_dwordx2 v[0:1], v[2:3], off
	v_cvt_pk_bf16_f32 v2, v98, v99
	v_cvt_pk_bf16_f32 v3, v100, v101
	global_store_dwordx2 v[0:1], v[2:3], off offset:32
	v_cvt_pk_bf16_f32 v2, v90, v91
	v_cvt_pk_bf16_f32 v3, v92, v93
	global_store_dwordx2 v[0:1], v[2:3], off offset:64
	v_cvt_pk_bf16_f32 v2, v74, v75
	v_cvt_pk_bf16_f32 v3, v76, v77
	s_mov_b64 s[10:11], 0
	global_store_dwordx2 v[0:1], v[2:3], off offset:96

.LBB0_380:
	s_andn2_saveexec_b64 s[62:63], s[0:1]
	s_cbranch_execz .LBB0_433
	v_mov_b32_e32 v0, v217
	s_nop 0
	v_cmp_eq_u32_e32 vcc, 0, v0
	s_and_saveexec_b64 s[0:1], vcc
	ds_write_b32 v227, v17
	s_or_b64 exec, exec, s[0:1]
	v_ashrrev_i32_e32 v1, 8, v5
	v_and_b32_e32 v11, 3, v4
	s_waitcnt vmcnt(1)
	v_lshl_or_b32 v2, v1, 2, v11
	s_mov_b32 s0, 0x90000
	v_mul_lo_u32 v2, v2, s0
	v_bfe_u32 v10, v4, 2, 6
	v_ashrrev_i32_e32 v3, 31, v2
	v_mov_b64_e32 v[4:5], 0x400000
	v_lshl_add_u64 v[2:3], v[2:3], 1, v[4:5]
	v_med3_u32 v4, v10, 4, 60
	v_readlane_b32 s0, v254, 31
	v_add_u32_e32 v128, -4, v4
	v_readlane_b32 s1, v254, 32
	v_ashrrev_i32_e32 v129, 2, v0
	v_lshl_add_u32 v6, v128, 6, v129
	v_lshl_add_u64 v[4:5], s[0:1], 0, v[2:3]
	v_readlane_b32 s0, v254, 29
	v_readlane_b32 s1, v254, 30
	v_ashrrev_i32_e32 v7, 31, v6
	v_lshlrev_b32_e32 v13, 5, v0
	v_lshl_add_u64 v[2:3], s[0:1], 0, v[2:3]
	v_ashrrev_i32_e32 v12, 1, v0
	v_lshlrev_b64 v[6:7], 8, v[6:7]
	v_and_b32_e32 v8, 0x60, v13
	s_movk_i32 s0, 0x2400
	v_lshl_add_u64 v[6:7], v[4:5], 0, v[6:7]
	v_lshlrev_b32_e32 v116, 1, v8
	v_mov_b32_e32 v117, v17
	v_mad_i64_i32 v[2:3], s[0:1], v12, s0, v[2:3]
	v_lshlrev_b32_e32 v8, 7, v128
	v_mov_b32_e32 v9, v17
	v_and_b32_e32 v13, 32, v13
	v_lshl_add_u64 v[6:7], v[6:7], 0, v[116:117]
	v_lshl_add_u64 v[8:9], v[2:3], 0, v[8:9]
	v_lshlrev_b32_e32 v118, 1, v13
	v_mov_b32_e32 v119, v17
	v_readlane_b32 s0, v254, 60
	v_lshl_add_u64 v[8:9], v[8:9], 0, v[118:119]
	global_load_dwordx4 v[20:23], v[6:7], off
	global_load_dwordx4 v[28:31], v[8:9], off
	global_load_dwordx4 v[24:27], v[6:7], off offset:16
	global_load_dwordx4 v[32:35], v[8:9], off offset:16
	global_load_dwordx4 v[36:39], v[6:7], off offset:32
	global_load_dwordx4 v[44:47], v[8:9], off offset:32
	global_load_dwordx4 v[40:43], v[6:7], off offset:48
	global_load_dwordx4 v[48:51], v[8:9], off offset:48
	v_lshlrev_b32_e32 v7, 6, v10
	v_lshlrev_b32_e32 v16, 8, v11
	v_or_b32_e32 v11, s0, v11
	s_movk_i32 s0, 0x88
	v_and_b32_e32 v9, 15, v0
	v_bfe_u32 v6, v0, 4, 2
	v_mul_lo_u32 v15, v129, s0
	s_movk_i32 s0, 0x44
	v_lshl_or_b32 v1, v1, 12, v7
	v_bfi_b32 v13, -16, v129, v0
	v_lshlrev_b32_e32 v14, 3, v6
	v_mul_lo_u32 v12, v12, s0
	v_lshlrev_b32_e32 v130, 2, v6
	v_mul_u32_u24_e32 v6, 0x88, v9
	s_movk_i32 s0, 0x4400
	v_mul_lo_u32 v1, v1, s33
	v_med3_i32 v7, v13, 8, 56
	v_add3_u32 v133, v6, v14, s0
	v_add_u32_e32 v6, 0x1800000, v1
	v_lshlrev_b32_e32 v131, 1, v15
	v_add_u32_e32 v15, -8, v7
	v_add_u32_e32 v18, 8, v7
	v_ashrrev_i32_e32 v7, 31, v6
	v_lshl_add_u64 v[6:7], s[30:31], 0, v[6:7]
	v_lshl_add_u64 v[122:123], v[4:5], 0, v[116:117]
	v_lshl_add_u64 v[4:5], v[6:7], 0, v[16:17]
	v_mul_u32_u24_e32 v16, 0x744, v11
	v_lshl_add_u64 v[126:127], s[16:17], 0, v[16:17]
	v_mad_i64_i32 v[120:121], s[0:1], v13, s33, v[4:5]
	v_and_b32_e32 v16, 48, v0
	v_and_b32_e32 v8, 63, v0
	v_lshl_add_u64 v[0:1], v[120:121], 0, v[16:17]
	global_load_dwordx4 v[52:55], v[0:1], off offset:3072
	global_load_dwordx4 v[56:59], v[0:1], off offset:3136
	global_load_dwordx4 v[60:63], v[0:1], off offset:3200
	global_load_dwordx4 v[64:67], v[0:1], off offset:3264
	v_sub_u32_e32 v0, v130, v13
	v_lshl_add_u64 v[124:125], v[2:3], 0, v[118:119]
	v_med3_i32 v119, v0, -15, 15
	v_or_b32_e32 v0, 1, v130
	v_cmp_ge_u32_e64 s[46:47], v0, v15
	v_sub_u32_e32 v0, v0, v13
	v_med3_i32 v135, v0, -15, 15
	v_or_b32_e32 v0, 2, v130
	v_cmp_ge_u32_e64 s[48:49], v0, v15
	v_sub_u32_e32 v0, v0, v13
	v_med3_i32 v136, v0, -15, 15
	v_or_b32_e32 v0, 3, v130
	v_cmp_ge_u32_e64 s[50:51], v0, v15
	v_sub_u32_e32 v0, v0, v13
	s_movk_i32 s0, 0x110
	v_med3_i32 v137, v0, -15, 15
	v_or_b32_e32 v0, 16, v130
	v_mad_u32_u24 v117, v9, s0, v16
	v_cmp_ge_u32_e32 vcc, v0, v15
	v_cmp_lt_u32_e64 s[0:1], v0, v18
	v_sub_u32_e32 v0, v0, v13
	v_med3_i32 v138, v0, -15, 15
	v_or_b32_e32 v0, 17, v130
	s_and_b64 s[64:65], vcc, s[0:1]
	v_cmp_ge_u32_e32 vcc, v0, v15
	v_cmp_lt_u32_e64 s[0:1], v0, v18
	v_sub_u32_e32 v0, v0, v13
	v_med3_i32 v139, v0, -15, 15
	v_or_b32_e32 v0, 18, v130
	s_and_b64 s[66:67], vcc, s[0:1]
	v_cmp_ge_u32_e32 vcc, v0, v15
	v_cmp_lt_u32_e64 s[0:1], v0, v18
	v_sub_u32_e32 v0, v0, v13
	v_med3_i32 v140, v0, -15, 15
	v_or_b32_e32 v0, 19, v130
	s_and_b64 s[68:69], vcc, s[0:1]
	v_cmp_ge_u32_e32 vcc, v0, v15
	v_cmp_lt_u32_e64 s[0:1], v0, v18
	v_sub_u32_e32 v0, v0, v13
	v_med3_i32 v141, v0, -15, 15
	v_or_b32_e32 v0, 32, v130
	s_and_b64 s[70:71], vcc, s[0:1]
	v_cmp_ge_u32_e32 vcc, v0, v15
	v_cmp_lt_u32_e64 s[0:1], v0, v18
	v_sub_u32_e32 v0, v0, v13
	v_med3_i32 v142, v0, -15, 15
	v_or_b32_e32 v0, 33, v130
	s_and_b64 s[72:73], vcc, s[0:1]
	v_cmp_ge_u32_e32 vcc, v0, v15
	v_cmp_lt_u32_e64 s[0:1], v0, v18
	v_sub_u32_e32 v0, v0, v13
	v_med3_i32 v143, v0, -15, 15
	v_or_b32_e32 v0, 34, v130
	s_and_b64 s[74:75], vcc, s[0:1]
	v_cmp_ge_u32_e32 vcc, v0, v15
	v_cmp_lt_u32_e64 s[0:1], v0, v18
	v_sub_u32_e32 v0, v0, v13
	v_med3_i32 v144, v0, -15, 15
	v_or_b32_e32 v0, 35, v130
	s_and_b64 s[76:77], vcc, s[0:1]
	v_cmp_ge_u32_e32 vcc, v0, v15
	v_cmp_lt_u32_e64 s[0:1], v0, v18
	v_sub_u32_e32 v0, v0, v13
	v_med3_i32 v145, v0, -15, 15
	v_or_b32_e32 v0, 48, v130
	v_cmp_lt_u32_e64 s[52:53], v0, v18
	v_sub_u32_e32 v0, v0, v13
	v_med3_i32 v146, v0, -15, 15
	v_or_b32_e32 v0, 49, v130
	v_cmp_lt_u32_e64 s[54:55], v0, v18
	v_sub_u32_e32 v0, v0, v13
	v_med3_i32 v147, v0, -15, 15
	v_or_b32_e32 v0, 50, v130
	v_cmp_lt_u32_e64 s[56:57], v0, v18
	v_sub_u32_e32 v0, v0, v13
	v_med3_i32 v148, v0, -15, 15
	v_or_b32_e32 v0, 51, v130
	v_cmp_lt_u32_e64 s[58:59], v0, v18
	v_mov_b32_e32 v18, v17
	v_mov_b32_e32 v19, v17
	v_sub_u32_e32 v0, v0, v13
	v_mov_b32_e32 v16, v17
	v_mov_b64_e32 v[74:75], v[18:19]
	v_mov_b64_e32 v[82:83], v[18:19]
	v_mov_b64_e32 v[86:87], v[18:19]
	v_mov_b64_e32 v[90:91], v[18:19]
	v_mov_b64_e32 v[94:95], v[18:19]
	v_mov_b64_e32 v[98:99], v[18:19]
	v_mov_b64_e32 v[78:79], v[18:19]
	v_mov_b64_e32 v[70:71], v[18:19]
	v_lshlrev_b32_e32 v132, 1, v12
	v_add3_u32 v12, v194, v131, v116
	v_sub_u32_e32 v134, v128, v10
	s_mov_b32 s83, 0
	v_cmp_eq_u32_e64 s[42:43], 0, v8
	v_cmp_ge_u32_e64 s[44:45], v130, v15
	s_and_b64 s[0:1], vcc, s[0:1]
	v_med3_i32 v149, v0, -15, 15
	v_mov_b32_e32 v151, 0xff800000
	v_mov_b32_e32 v150, 0
	v_mov_b64_e32 v[72:73], v[16:17]
	v_mov_b64_e32 v[80:81], v[16:17]
	v_mov_b64_e32 v[84:85], v[16:17]
	v_mov_b64_e32 v[88:89], v[16:17]
	v_mov_b64_e32 v[92:93], v[16:17]
	v_mov_b64_e32 v[96:97], v[16:17]
	v_mov_b64_e32 v[76:77], v[16:17]
	v_mov_b64_e32 v[68:69], v[16:17]
	s_mov_b32 s34, 0
	v_add3_u32 v14, v194, v132, v118
	s_waitcnt vmcnt(11)
	ds_write_b128 v12, v[20:23]
	s_waitcnt vmcnt(10)
	ds_write_b64 v14, v[28:29] offset:17408
	ds_write_b64 v14, v[30:31] offset:17416
	s_waitcnt vmcnt(9)
	ds_write_b128 v12, v[24:27] offset:16
	s_waitcnt vmcnt(8)
	ds_write_b64 v14, v[32:33] offset:17424
	ds_write_b64 v14, v[34:35] offset:17432
	s_waitcnt vmcnt(7)
	ds_write_b128 v12, v[36:39] offset:32
	s_waitcnt vmcnt(6)
	ds_write_b64 v14, v[44:45] offset:17440
	ds_write_b64 v14, v[46:47] offset:17448
	s_waitcnt vmcnt(5)
	ds_write_b128 v12, v[40:43] offset:48
	s_waitcnt vmcnt(4)
	ds_write_b64 v14, v[48:49] offset:17456
	ds_write_b64 v14, v[50:51] offset:17464
	s_waitcnt vmcnt(0) lgkmcnt(0)
	s_barrier
.LBB0_384:
	s_add_i32 s82, s83, 1
	s_cmp_lg_u32 s83, 15
	s_cselect_b64 s[78:79], -1, 0
	s_cmp_eq_u32 s83, 15
	s_cbranch_scc1 .LBB0_386
	s_cmp_gt_u32 s83, 7
	s_cbranch_scc1 .Lna_pf_skip
	v_add_u32_e32 v188, s83, v134
	s_movk_i32 s40, 0xe8
	v_mad_i32_i24 v188, v188, 31, s40
	v_readfirstlane_b32 s40, v126
	v_readfirstlane_b32 s41, v127
	v_add_lshl_u32 v172, v188, v119, 2
	v_add_lshl_u32 v173, v188, v135, 2
	v_add_lshl_u32 v174, v188, v136, 2
	v_add_lshl_u32 v175, v188, v137, 2
	v_add_lshl_u32 v176, v188, v138, 2
	v_add_lshl_u32 v177, v188, v139, 2
	v_add_lshl_u32 v178, v188, v140, 2
	v_add_lshl_u32 v179, v188, v141, 2
	v_add_lshl_u32 v180, v188, v142, 2
	v_add_lshl_u32 v181, v188, v143, 2
	v_add_lshl_u32 v182, v188, v144, 2
	v_add_lshl_u32 v183, v188, v145, 2
	v_add_lshl_u32 v184, v188, v146, 2
	v_add_lshl_u32 v185, v188, v147, 2
	v_add_lshl_u32 v186, v188, v148, 2
	v_add_lshl_u32 v187, v188, v149, 2
	global_load_dword v172, v172, s[40:41]
	global_load_dword v173, v173, s[40:41]
	global_load_dword v174, v174, s[40:41]
	global_load_dword v175, v175, s[40:41]
	global_load_dword v176, v176, s[40:41]
	global_load_dword v177, v177, s[40:41]
	global_load_dword v178, v178, s[40:41]
	global_load_dword v179, v179, s[40:41]
	global_load_dword v180, v180, s[40:41]
	global_load_dword v181, v181, s[40:41]
	global_load_dword v182, v182, s[40:41]
	global_load_dword v183, v183, s[40:41]
	global_load_dword v184, v184, s[40:41]
	global_load_dword v185, v185, s[40:41]
	global_load_dword v186, v186, s[40:41]
	global_load_dword v187, v187, s[40:41]
.Lna_pf_skip:
	s_cmp_lt_u32 s83, 7
	s_cselect_b64 vcc, -1, 0
	s_lshl_b32 s40, s83, 6
	s_addk_i32 s40, 0xe40
	v_add_lshl_u32 v0, s82, v128, 6
	v_mov_b32_e32 v1, s40
	v_cndmask_b32_e32 v0, v1, v0, vcc
	v_add_u32_e32 v2, v0, v129
	v_ashrrev_i32_e32 v3, 31, v2
	v_lshlrev_b64 v[2:3], 8, v[2:3]
	v_lshl_add_u64 v[2:3], v[122:123], 0, v[2:3]
	v_ashrrev_i32_e32 v1, 31, v0
	v_lshl_add_u64 v[0:1], v[0:1], 1, v[124:125]
	global_load_dwordx4 v[20:23], v[2:3], off
	global_load_dwordx4 v[24:27], v[2:3], off offset:16
	global_load_dwordx4 v[28:31], v[0:1], off
	global_load_dwordx4 v[32:35], v[0:1], off offset:16
	global_load_dwordx4 v[36:39], v[2:3], off offset:32
	global_load_dwordx4 v[40:43], v[2:3], off offset:48
	global_load_dwordx4 v[44:47], v[0:1], off offset:32
	global_load_dwordx4 v[48:51], v[0:1], off offset:48
.LBB0_386:
	s_bitcmp1_b32 s83, 0
	s_cselect_b32 s40, 0x8c00, 0
	v_add_u32_e32 v18, s40, v194
	v_add_u32_e32 v16, v117, v18
	ds_read_b128 v[0:3], v16 offset:0
	ds_read_b128 v[4:7], v16 offset:64
	ds_read_b128 v[8:11], v16 offset:128
	ds_read_b128 v[12:15], v16 offset:192
	ds_read_b128 v[100:103], v16 offset:4352
	ds_read_b128 v[108:111], v16 offset:4416
	ds_read_b128 v[152:155], v16 offset:4480
	ds_read_b128 v[156:159], v16 offset:4544
	s_mov_b64 s[80:81], -1
	s_waitcnt lgkmcnt(4)
	ds_read_b128 v[104:107], v16 offset:8704
	ds_read_b128 v[160:163], v16 offset:8768
	ds_read_b128 v[164:167], v16 offset:8832
	ds_read_b128 v[168:171], v16 offset:8896
	s_waitcnt lgkmcnt(4)
	v_mfma_f32_16x16x32_bf16 v[0:3], v[0:3], v[52:55], 0
	s_cmp_lt_u32 s83, 8
	v_mfma_f32_16x16x32_bf16 v[0:3], v[4:7], v[56:59], v[0:3]
	v_mfma_f32_16x16x32_bf16 v[0:3], v[8:11], v[60:63], v[0:3]
	v_mfma_f32_16x16x32_bf16 v[112:115], v[12:15], v[64:67], v[0:3]
	ds_read_b128 v[0:3], v16 offset:13056
	ds_read_b128 v[4:7], v16 offset:13120
	ds_read_b128 v[8:11], v16 offset:13184
	ds_read_b128 v[12:15], v16 offset:13248
	s_waitcnt lgkmcnt(4)
	v_mfma_f32_16x16x32_bf16 v[100:103], v[100:103], v[52:55], 0
	s_waitcnt lgkmcnt(0)
	v_mfma_f32_16x16x32_bf16 v[104:107], v[104:107], v[52:55], 0
	s_nop 3
	v_mfma_f32_16x16x32_bf16 v[0:3], v[0:3], v[52:55], 0
	v_mfma_f32_16x16x32_bf16 v[104:107], v[160:163], v[56:59], v[104:107]
	v_mfma_f32_16x16x32_bf16 v[100:103], v[108:111], v[56:59], v[100:103]
	v_mfma_f32_16x16x32_bf16 v[0:3], v[4:7], v[56:59], v[0:3]
	v_mfma_f32_16x16x32_bf16 v[104:107], v[164:167], v[60:63], v[104:107]
	v_mfma_f32_16x16x32_bf16 v[100:103], v[152:155], v[60:63], v[100:103]
	v_mfma_f32_16x16x32_bf16 v[0:3], v[8:11], v[60:63], v[0:3]
	v_mfma_f32_16x16x32_bf16 v[104:107], v[168:171], v[64:67], v[104:107]
	v_mfma_f32_16x16x32_bf16 v[108:111], v[156:159], v[64:67], v[100:103]
	v_mfma_f32_16x16x32_bf16 v[100:103], v[12:15], v[64:67], v[0:3]
	s_cbranch_scc0 .LBB0_398
	s_andn2_b64 vcc, exec, s[80:81]
	s_cbranch_vccz .LBB0_399

.LBB0_390:
	v_cvt_pk_bf16_f32 v0, v0, v1
	v_cvt_pk_bf16_f32 v1, v2, v3
	v_cvt_pk_bf16_f32 v2, v4, v5
	v_cvt_pk_bf16_f32 v3, v6, v7
	v_cvt_pk_bf16_f32 v4, v8, v9
	v_cvt_pk_bf16_f32 v5, v10, v11
	v_cvt_pk_bf16_f32 v6, v12, v13
	v_add_u32_e32 v12, v133, v18
	ds_read2_b64 v[8:11], v12 offset1:4
	ds_read2_b64 v[100:103], v12 offset0:8 offset1:12
	v_add_u32_e32 v13, 0x880, v12
	ds_read2_b64 v[104:107], v13 offset1:4
	ds_read2_b64 v[108:111], v13 offset0:8 offset1:12
	v_exp_f32_e32 v15, v15
	s_waitcnt lgkmcnt(3)
	v_add_u32_e32 v13, 0x1100, v12
	v_mfma_f32_16x16x32_bf16 v[8:11], v[8:11], v[0:3], v[96:99]
	ds_read2_b64 v[112:115], v13 offset1:4
	v_cvt_pk_bf16_f32 v7, v14, v15
	s_waitcnt lgkmcnt(3)
	s_andn2_b64 vcc, exec, s[78:79]
	s_nop 0
	v_mfma_f32_16x16x32_bf16 v[96:99], v[100:103], v[4:7], v[8:11]
	ds_read2_b64 v[8:11], v13 offset0:8 offset1:12
	s_waitcnt lgkmcnt(3)
	v_add_u32_e32 v13, 0x1980, v12
	ds_read2_b64 v[100:103], v13 offset1:4
	v_mfma_f32_16x16x32_bf16 v[92:95], v[104:107], v[0:3], v[92:95]
	s_waitcnt lgkmcnt(3)
	ds_read2_b64 v[104:107], v13 offset0:8 offset1:12
	s_waitcnt lgkmcnt(3)
	v_add_u32_e32 v13, 0x2200, v12
	v_mfma_f32_16x16x32_bf16 v[88:91], v[112:115], v[0:3], v[88:91]
	v_mfma_f32_16x16x32_bf16 v[92:95], v[108:111], v[4:7], v[92:95]
	ds_read2_b64 v[108:111], v13 offset1:4
	s_waitcnt lgkmcnt(3)
	s_nop 0
	v_mfma_f32_16x16x32_bf16 v[88:91], v[8:11], v[4:7], v[88:91]
	ds_read2_b64 v[8:11], v13 offset0:8 offset1:12
	s_waitcnt lgkmcnt(3)
	v_add_u32_e32 v13, 0x2a80, v12
	v_mfma_f32_16x16x32_bf16 v[84:87], v[100:103], v[0:3], v[84:87]
	ds_read2_b64 v[100:103], v13 offset1:4
	s_waitcnt lgkmcnt(3)
	s_nop 0
	v_mfma_f32_16x16x32_bf16 v[84:87], v[104:107], v[4:7], v[84:87]
	ds_read2_b64 v[104:107], v13 offset0:8 offset1:12
	s_waitcnt lgkmcnt(3)
	v_add_u32_e32 v13, 0x3300, v12
	v_mfma_f32_16x16x32_bf16 v[80:83], v[108:111], v[0:3], v[80:83]
	ds_read2_b64 v[108:111], v13 offset1:4
	s_waitcnt lgkmcnt(3)
	v_add_u32_e32 v12, 0x3b80, v12
	v_mfma_f32_16x16x32_bf16 v[80:83], v[8:11], v[4:7], v[80:83]
	ds_read2_b64 v[8:11], v13 offset0:8 offset1:12
	s_waitcnt lgkmcnt(3)
	s_nop 0
	v_mfma_f32_16x16x32_bf16 v[72:75], v[100:103], v[0:3], v[72:75]
	ds_read2_b64 v[100:103], v12 offset1:4
	s_waitcnt lgkmcnt(3)
	s_nop 0
	v_mfma_f32_16x16x32_bf16 v[72:75], v[104:107], v[4:7], v[72:75]
	ds_read2_b64 v[104:107], v12 offset0:8 offset1:12
	s_waitcnt lgkmcnt(3)
	s_waitcnt lgkmcnt(2)
	s_waitcnt lgkmcnt(1)
	s_nop 0
	v_mfma_f32_16x16x32_bf16 v[76:79], v[108:111], v[0:3], v[76:79]
	s_waitcnt lgkmcnt(0)
	v_mfma_f32_16x16x32_bf16 v[0:3], v[100:103], v[0:3], v[68:71]
	v_mfma_f32_16x16x32_bf16 v[76:79], v[8:11], v[4:7], v[76:79]
	v_mfma_f32_16x16x32_bf16 v[68:71], v[104:107], v[4:7], v[0:3]
	s_cbranch_vccnz .LBB0_392
	s_bitcmp1_b32 s82, 0
	s_cselect_b32 s40, 0x8c00, 0
	s_nop 2
	v_add_u32_e32 v0, s40, v194
	v_add3_u32 v1, v0, v131, v116
	v_add3_u32 v0, v0, v132, v118
	s_waitcnt vmcnt(0)
	ds_write_b128 v1, v[20:23]
	ds_write_b64 v0, v[28:29] offset:17408
	ds_write_b64 v0, v[30:31] offset:17416
	ds_write_b128 v1, v[24:27] offset:16
	ds_write_b64 v0, v[32:33] offset:17424
	ds_write_b64 v0, v[34:35] offset:17432
	ds_write_b128 v1, v[36:39] offset:32
	ds_write_b64 v0, v[44:45] offset:17440
	ds_write_b64 v0, v[46:47] offset:17448
	ds_write_b128 v1, v[40:43] offset:48
	ds_write_b64 v0, v[48:49] offset:17456
	ds_write_b64 v0, v[50:51] offset:17464

.LBB0_399:
	s_nop 1
	v_add_u32_e32 v2, s83, v134
	v_mov_b64_e32 v[0:1], 0xe8
	v_mad_u64_u32 v[0:1], s[40:41], v2, 31, v[0:1]
	v_mov_b32_e32 v19, 0xff800000
	v_mul_f32_e32 v112, s94, v112
	v_mul_f32_e32 v113, s94, v113
	v_mul_f32_e32 v114, s94, v114
	v_mul_f32_e32 v115, s94, v115
	v_mul_f32_e32 v108, s94, v108
	v_mul_f32_e32 v109, s94, v109
	v_mul_f32_e32 v110, s94, v110
	v_mul_f32_e32 v111, s94, v111
	v_mul_f32_e32 v104, s94, v104
	v_mul_f32_e32 v105, s94, v105
	v_mul_f32_e32 v106, s94, v106
	v_mul_f32_e32 v107, s94, v107
	v_mul_f32_e32 v100, s94, v100
	v_mul_f32_e32 v101, s94, v101
	v_mul_f32_e32 v102, s94, v102
	v_mul_f32_e32 v103, s94, v103
	s_waitcnt vmcnt(8)
	v_mul_f32_e32 v2, s95, v172
	v_add_f32_e32 v2, v112, v2
	v_cndmask_b32_e64 v2, v19, v2, s[44:45]
	v_mul_f32_e32 v1, s95, v173
	v_add_f32_e32 v1, v113, v1
	v_cndmask_b32_e64 v1, v19, v1, s[46:47]
	v_mul_f32_e32 v4, s95, v174
	v_add_f32_e32 v4, v114, v4
	v_cndmask_b32_e64 v4, v19, v4, s[48:49]
	v_mul_f32_e32 v3, s95, v175
	v_add_f32_e32 v3, v115, v3
	v_cndmask_b32_e64 v3, v19, v3, s[50:51]
	v_mul_f32_e32 v6, s95, v176
	v_add_f32_e32 v6, v108, v6
	v_cndmask_b32_e64 v6, v19, v6, s[64:65]
	v_mul_f32_e32 v5, s95, v177
	v_add_f32_e32 v5, v109, v5
	v_cndmask_b32_e64 v5, v19, v5, s[66:67]
	v_mul_f32_e32 v8, s95, v178
	v_add_f32_e32 v8, v110, v8
	v_cndmask_b32_e64 v8, v19, v8, s[68:69]
	v_mul_f32_e32 v7, s95, v179
	v_add_f32_e32 v7, v111, v7
	v_cndmask_b32_e64 v7, v19, v7, s[70:71]
	v_mul_f32_e32 v10, s95, v180
	v_add_f32_e32 v10, v104, v10
	v_cndmask_b32_e64 v10, v19, v10, s[72:73]
	v_mul_f32_e32 v9, s95, v181
	v_add_f32_e32 v9, v105, v9
	v_cndmask_b32_e64 v9, v19, v9, s[74:75]
	v_mul_f32_e32 v12, s95, v182
	v_add_f32_e32 v12, v106, v12
	v_cndmask_b32_e64 v12, v19, v12, s[76:77]
	v_mul_f32_e32 v11, s95, v183
	v_add_f32_e32 v11, v107, v11
	v_cndmask_b32_e64 v11, v19, v11, s[0:1]
	v_mul_f32_e32 v14, s95, v184
	v_add_f32_e32 v14, v100, v14
	v_cndmask_b32_e64 v14, v19, v14, s[52:53]
	v_mul_f32_e32 v13, s95, v185
	v_add_f32_e32 v13, v101, v13
	v_cndmask_b32_e64 v13, v19, v13, s[54:55]
	v_mul_f32_e32 v16, s95, v186
	v_add_f32_e32 v16, v102, v16
	v_cndmask_b32_e64 v16, v19, v16, s[56:57]
	v_mul_f32_e32 v15, s95, v187
	v_add_f32_e32 v15, v103, v15
	v_cndmask_b32_e64 v15, v19, v15, s[58:59]
	s_mov_b32 s40, 0xff800000
	v_max3_f32 v0, v2, s40, v1
	v_max3_f32 v0, v0, v4, v3
	v_max3_f32 v0, v0, v6, v5
	v_max3_f32 v0, v0, v8, v7
	v_max3_f32 v0, v0, v10, v9
	v_max3_f32 v0, v0, v12, v11
	v_cmp_lt_i32_e32 vcc, v222, v220
	v_max3_f32 v0, v0, v14, v13
	v_max3_f32 v0, v0, v16, v15
	v_cndmask_b32_e32 v19, v218, v222, vcc
	v_lshlrev_b32_e32 v19, 2, v19
	ds_bpermute_b32 v19, v19, v0
	v_cmp_lt_i32_e32 vcc, v221, v220
	s_waitcnt lgkmcnt(0)
	v_max_f32_e32 v19, v19, v19
	v_max_f32_e32 v0, v0, v19
	v_cndmask_b32_e32 v19, v218, v221, vcc
	v_lshlrev_b32_e32 v19, 2, v19
	ds_bpermute_b32 v19, v19, v0
	s_waitcnt lgkmcnt(0)
	v_max3_f32 v19, v151, v0, v19
	v_sub_f32_e32 v0, v2, v19
	v_sub_f32_e32 v1, v1, v19
	v_exp_f32_e32 v0, v0
	v_sub_f32_e32 v2, v4, v19
	v_exp_f32_e32 v1, v1
	v_exp_f32_e32 v2, v2
	v_add_f32_e32 v4, 0, v0
	v_sub_f32_e32 v3, v3, v19
	v_add_f32_e32 v4, v1, v4
	v_add_f32_e32 v100, v2, v4
	v_exp_f32_e32 v3, v3
	v_sub_f32_e32 v4, v6, v19
	v_exp_f32_e32 v4, v4
	v_sub_f32_e32 v5, v5, v19
	v_exp_f32_e32 v5, v5
	v_sub_f32_e32 v6, v8, v19
	v_exp_f32_e32 v6, v6
	v_add_f32_e32 v8, v3, v100
	v_add_f32_e32 v8, v4, v8
	v_add_f32_e32 v8, v5, v8
	v_sub_f32_e32 v7, v7, v19
	v_add_f32_e32 v100, v6, v8
	v_exp_f32_e32 v7, v7
	v_sub_f32_e32 v8, v10, v19
	v_exp_f32_e32 v8, v8
	v_sub_f32_e32 v9, v9, v19
	v_exp_f32_e32 v9, v9
	v_sub_f32_e32 v10, v12, v19
	v_exp_f32_e32 v10, v10
	v_add_f32_e32 v12, v7, v100
	v_add_f32_e32 v12, v8, v12
	v_add_f32_e32 v12, v9, v12
	v_sub_f32_e32 v11, v11, v19
	v_add_f32_e32 v100, v10, v12
	v_exp_f32_e32 v11, v11
	v_sub_f32_e32 v12, v14, v19
	v_exp_f32_e32 v12, v12
	v_sub_f32_e32 v13, v13, v19
	v_exp_f32_e32 v13, v13
	v_sub_f32_e32 v14, v16, v19
	v_exp_f32_e32 v14, v14
	v_add_f32_e32 v16, v11, v100
	v_add_f32_e32 v16, v12, v16
	v_add_f32_e32 v16, v13, v16
	v_add_f32_e32 v152, v14, v16
	v_sub_f32_e32 v15, v15, v19
	v_sub_f32_e32 v16, v151, v19
	v_exp_f32_e32 v16, v16
	s_nop 0
	v_cmp_neq_f32_e32 vcc, 1.0, v16
	s_cbranch_vccnz .LBB0_389
	s_branch .LBB0_390

.LBB0_1140:
	s_getreg_b32 s0, hwreg(HW_REG_XCC_ID, 0, 4)
	s_and_b32 s34, s0, 7
	s_add_i32 s0, s42, 24
	s_ashr_i32 s1, s0, 31
	s_lshl_b64 s[0:1], s[0:1], 2
	v_readlane_b32 s40, v252, 55
	v_readlane_b32 s41, v252, 56
	s_add_u32 s0, s40, s0
	s_addc_u32 s1, s41, s1
	v_mov_b32_e32 v199, 0
	v_mov_b32_e32 v16, s34
	s_mov_b32 s99, 0
	s_branch .LBB0_1142

.Lpfa_skip_m1:
	s_mov_b32 s99, 1
	v_and_b32_e32 v70, 0xc0, v203
	v_or_b32_e32 v71, s34, v238
	v_max_f32_e32 v78, v160, v160
	v_max_f32_e32 v79, v161, v161
	v_add_u32_e32 v72, v71, v239
	v_or_b32_e32 v82, s43, v70
	v_max_f32_e32 v70, v158, v158
	v_max_f32_e32 v71, v159, v159
	v_max_f32_e32 v78, 0, v78
	v_max_f32_e32 v79, 0, v79
	v_max_f32_e32 v70, 0, v70
	v_max_f32_e32 v71, 0, v71
	v_pk_mul_f32 v[78:79], v[78:79], v[78:79]
	v_lshrrev_b32_e32 v86, 5, v82
	v_ashrrev_i32_e32 v73, 31, v72
	v_pk_mul_f32 v[70:71], v[70:71], v[70:71]
	v_cvt_pk_bf16_f32 v81, v78, v79
	v_mul_u32_u24_e32 v78, 0x9000, v86
	v_mov_b32_e32 v79, v17
	v_cvt_pk_bf16_f32 v80, v70, v71
	v_lshl_add_u64 v[70:71], v[78:79], 0, v[72:73]
	v_lshlrev_b64 v[70:71], 6, v[70:71]
	v_lshl_or_b32 v118, v201, 2, v82
	v_lshl_add_u64 v[82:83], s[30:31], 0, v[70:71]
	v_lshlrev_b32_e32 v70, 3, v201
	v_mov_b32_e32 v71, v17
	v_lshl_add_u64 v[82:83], v[82:83], 0, v[70:71]
	global_store_dwordx2 v[82:83], v[80:81], off
	v_max_f32_e32 v80, v154, v154
	v_max_f32_e32 v81, v155, v155
	v_max_f32_e32 v84, v156, v156
	v_max_f32_e32 v85, v157, v157
	v_max_f32_e32 v80, 0, v80
	v_max_f32_e32 v81, 0, v81
	v_max_f32_e32 v84, 0, v84
	v_max_f32_e32 v85, 0, v85
	v_pk_mul_f32 v[80:81], v[80:81], v[80:81]
	v_pk_mul_f32 v[84:85], v[84:85], v[84:85]
	v_cvt_pk_bf16_f32 v80, v80, v81
	v_cvt_pk_bf16_f32 v81, v84, v85
	global_store_dwordx2 v[82:83], v[80:81], off offset:32
	v_max_f32_e32 v80, v150, v150
	v_max_f32_e32 v81, v151, v151
	v_max_f32_e32 v80, 0, v80
	v_max_f32_e32 v81, 0, v81
	v_max_f32_e32 v82, v152, v152
	v_max_f32_e32 v83, v153, v153
	v_pk_mul_f32 v[80:81], v[80:81], v[80:81]
	v_max_f32_e32 v82, 0, v82
	v_max_f32_e32 v83, 0, v83
	s_mov_b32 s34, 0x9000
	v_pk_mul_f32 v[82:83], v[82:83], v[82:83]
	v_cvt_pk_bf16_f32 v84, v80, v81
	v_mad_u32_u24 v80, v86, s34, s34
	v_mov_b32_e32 v81, v17
	v_cvt_pk_bf16_f32 v85, v82, v83
	v_lshl_add_u64 v[82:83], v[80:81], 0, v[72:73]
	v_lshlrev_b64 v[82:83], 6, v[82:83]
	v_lshl_add_u64 v[82:83], s[30:31], 0, v[82:83]
	v_lshl_add_u64 v[82:83], v[82:83], 0, v[70:71]
	global_store_dwordx2 v[82:83], v[84:85], off
	v_max_f32_e32 v82, v146, v146
	v_max_f32_e32 v83, v147, v147
	v_max_f32_e32 v82, 0, v82
	v_max_f32_e32 v83, 0, v83
	v_pk_mul_f32 v[82:83], v[82:83], v[82:83]
	v_max_f32_e32 v84, v148, v148
	v_max_f32_e32 v85, v149, v149
	v_or_b32_e32 v88, 48, v118
	v_max_f32_e32 v84, 0, v84
	v_max_f32_e32 v85, 0, v85
	v_cvt_pk_bf16_f32 v86, v82, v83
	v_lshrrev_b32_e32 v82, 5, v88
	v_pk_mul_f32 v[84:85], v[84:85], v[84:85]
	v_mul_u32_u24_e32 v82, 0x9000, v82
	v_mov_b32_e32 v83, v17
	v_cvt_pk_bf16_f32 v87, v84, v85
	v_lshl_add_u64 v[84:85], v[82:83], 0, v[72:73]
	v_lshlrev_b64 v[84:85], 6, v[84:85]
	v_bitop3_b32 v73, v118, 28, 48 bitop3:0xc8
	v_lshl_add_u64 v[88:89], s[30:31], 0, v[84:85]
	v_lshlrev_b32_e32 v84, 1, v73
	v_mov_b32_e32 v85, v17
	v_lshl_add_u64 v[88:89], v[88:89], 0, v[84:85]
	v_max_f32_e32 v73, v142, v142
	global_store_dwordx2 v[88:89], v[86:87], off
	v_max_f32_e32 v88, 0, v73
	v_max_f32_e32 v73, v143, v143
	v_max_f32_e32 v89, 0, v73
	v_max_f32_e32 v73, v144, v144
	v_max_f32_e32 v118, 0, v73
	v_max_f32_e32 v73, v145, v145
	v_or_b32_e32 v86, 16, v72
	v_max_f32_e32 v119, 0, v73
	v_ashrrev_i32_e32 v87, 31, v86
	v_pk_mul_f32 v[88:89], v[88:89], v[88:89]
	v_pk_mul_f32 v[118:119], v[118:119], v[118:119]
	v_cvt_pk_bf16_f32 v88, v88, v89
	v_cvt_pk_bf16_f32 v89, v118, v119
	v_lshl_add_u64 v[118:119], v[78:79], 0, v[86:87]
	v_lshlrev_b64 v[118:119], 6, v[118:119]
	v_lshl_add_u64 v[118:119], s[30:31], 0, v[118:119]
	v_lshl_add_u64 v[118:119], v[118:119], 0, v[70:71]
	v_max_f32_e32 v73, v138, v138
	global_store_dwordx2 v[118:119], v[88:89], off
	v_max_f32_e32 v88, 0, v73
	v_max_f32_e32 v73, v139, v139
	v_max_f32_e32 v89, 0, v73
	v_max_f32_e32 v73, v140, v140
	v_max_f32_e32 v120, 0, v73
	v_max_f32_e32 v73, v141, v141
	v_max_f32_e32 v121, 0, v73
	v_pk_mul_f32 v[88:89], v[88:89], v[88:89]
	v_pk_mul_f32 v[120:121], v[120:121], v[120:121]
	v_cvt_pk_bf16_f32 v88, v88, v89
	v_cvt_pk_bf16_f32 v89, v120, v121
	v_max_f32_e32 v73, v134, v134
	global_store_dwordx2 v[118:119], v[88:89], off offset:32
	v_max_f32_e32 v88, 0, v73
	v_max_f32_e32 v73, v135, v135
	v_max_f32_e32 v89, 0, v73
	v_max_f32_e32 v73, v136, v136
	v_max_f32_e32 v118, 0, v73
	v_max_f32_e32 v73, v137, v137
	v_max_f32_e32 v119, 0, v73
	v_pk_mul_f32 v[88:89], v[88:89], v[88:89]
	v_pk_mul_f32 v[118:119], v[118:119], v[118:119]
	v_cvt_pk_bf16_f32 v88, v88, v89
	v_cvt_pk_bf16_f32 v89, v118, v119
	v_lshl_add_u64 v[118:119], v[80:81], 0, v[86:87]
	v_lshlrev_b64 v[118:119], 6, v[118:119]
	v_lshl_add_u64 v[118:119], s[30:31], 0, v[118:119]
	v_lshl_add_u64 v[118:119], v[118:119], 0, v[70:71]
	v_max_f32_e32 v73, v114, v114
	global_store_dwordx2 v[118:119], v[88:89], off
	v_max_f32_e32 v88, 0, v73
	v_max_f32_e32 v73, v115, v115
	v_max_f32_e32 v89, 0, v73
	v_max_f32_e32 v73, v116, v116
	v_max_f32_e32 v114, 0, v73
	v_max_f32_e32 v73, v117, v117
	v_lshl_add_u64 v[86:87], v[82:83], 0, v[86:87]
	v_max_f32_e32 v115, 0, v73
	v_lshlrev_b64 v[86:87], 6, v[86:87]
	v_pk_mul_f32 v[88:89], v[88:89], v[88:89]
	v_pk_mul_f32 v[114:115], v[114:115], v[114:115]
	v_lshl_add_u64 v[86:87], s[30:31], 0, v[86:87]
	v_cvt_pk_bf16_f32 v88, v88, v89
	v_cvt_pk_bf16_f32 v89, v114, v115
	v_lshl_add_u64 v[86:87], v[86:87], 0, v[84:85]
	v_max_f32_e32 v73, v110, v110
	global_store_dwordx2 v[86:87], v[88:89], off
	v_max_f32_e32 v88, 0, v73
	v_max_f32_e32 v73, v111, v111
	v_max_f32_e32 v89, 0, v73
	v_max_f32_e32 v73, v112, v112
	v_max_f32_e32 v110, 0, v73
	v_max_f32_e32 v73, v113, v113
	v_or_b32_e32 v86, 32, v72
	v_max_f32_e32 v111, 0, v73
	v_ashrrev_i32_e32 v87, 31, v86
	v_pk_mul_f32 v[88:89], v[88:89], v[88:89]
	v_pk_mul_f32 v[110:111], v[110:111], v[110:111]
	v_cvt_pk_bf16_f32 v88, v88, v89
	v_cvt_pk_bf16_f32 v89, v110, v111
	v_lshl_add_u64 v[110:111], v[78:79], 0, v[86:87]
	v_lshlrev_b64 v[110:111], 6, v[110:111]
	v_lshl_add_u64 v[110:111], s[30:31], 0, v[110:111]
	v_lshl_add_u64 v[110:111], v[110:111], 0, v[70:71]
	v_max_f32_e32 v73, v106, v106
	global_store_dwordx2 v[110:111], v[88:89], off
	v_max_f32_e32 v88, 0, v73
	v_max_f32_e32 v73, v107, v107
	v_max_f32_e32 v89, 0, v73
	v_max_f32_e32 v73, v108, v108
	v_max_f32_e32 v106, 0, v73
	v_max_f32_e32 v73, v109, v109
	v_max_f32_e32 v107, 0, v73
	v_pk_mul_f32 v[88:89], v[88:89], v[88:89]
	v_pk_mul_f32 v[106:107], v[106:107], v[106:107]
	v_cvt_pk_bf16_f32 v88, v88, v89
	v_cvt_pk_bf16_f32 v89, v106, v107
	v_max_f32_e32 v73, v102, v102
	global_store_dwordx2 v[110:111], v[88:89], off offset:32
	v_max_f32_e32 v88, 0, v73
	v_max_f32_e32 v73, v103, v103
	v_max_f32_e32 v89, 0, v73
	v_max_f32_e32 v73, v104, v104
	v_max_f32_e32 v102, 0, v73
	v_max_f32_e32 v73, v105, v105
	v_max_f32_e32 v103, 0, v73
	v_pk_mul_f32 v[88:89], v[88:89], v[88:89]
	v_pk_mul_f32 v[102:103], v[102:103], v[102:103]
	v_cvt_pk_bf16_f32 v88, v88, v89
	v_cvt_pk_bf16_f32 v89, v102, v103
	v_lshl_add_u64 v[102:103], v[80:81], 0, v[86:87]
	v_lshlrev_b64 v[102:103], 6, v[102:103]
	v_lshl_add_u64 v[102:103], s[30:31], 0, v[102:103]
	v_lshl_add_u64 v[102:103], v[102:103], 0, v[70:71]
	v_max_f32_e32 v73, v98, v98
	global_store_dwordx2 v[102:103], v[88:89], off
	v_max_f32_e32 v88, 0, v73
	v_max_f32_e32 v73, v99, v99
	v_max_f32_e32 v89, 0, v73
	v_max_f32_e32 v73, v100, v100
	v_max_f32_e32 v98, 0, v73
	v_max_f32_e32 v73, v101, v101
	v_lshl_add_u64 v[86:87], v[82:83], 0, v[86:87]
	v_max_f32_e32 v99, 0, v73
	v_lshlrev_b64 v[86:87], 6, v[86:87]
	v_pk_mul_f32 v[88:89], v[88:89], v[88:89]
	v_pk_mul_f32 v[98:99], v[98:99], v[98:99]
	v_lshl_add_u64 v[86:87], s[30:31], 0, v[86:87]
	v_cvt_pk_bf16_f32 v88, v88, v89
	v_cvt_pk_bf16_f32 v89, v98, v99
	v_lshl_add_u64 v[86:87], v[86:87], 0, v[84:85]
	v_max_f32_e32 v73, v94, v94
	global_store_dwordx2 v[86:87], v[88:89], off
	v_max_f32_e32 v88, 0, v73
	v_max_f32_e32 v73, v95, v95
	v_max_f32_e32 v89, 0, v73
	v_max_f32_e32 v73, v96, v96
	v_max_f32_e32 v94, 0, v73
	v_max_f32_e32 v73, v97, v97
	v_or_b32_e32 v86, 48, v72
	v_max_f32_e32 v95, 0, v73
	v_ashrrev_i32_e32 v87, 31, v86
	v_pk_mul_f32 v[88:89], v[88:89], v[88:89]
	v_pk_mul_f32 v[94:95], v[94:95], v[94:95]
	v_cvt_pk_bf16_f32 v88, v88, v89
	v_cvt_pk_bf16_f32 v89, v94, v95
	v_lshl_add_u64 v[94:95], v[78:79], 0, v[86:87]
	v_lshlrev_b64 v[94:95], 6, v[94:95]
	v_lshl_add_u64 v[94:95], s[30:31], 0, v[94:95]
	v_lshl_add_u64 v[94:95], v[94:95], 0, v[70:71]
	v_max_f32_e32 v73, v90, v90
	global_store_dwordx2 v[94:95], v[88:89], off
	v_max_f32_e32 v88, 0, v73
	v_max_f32_e32 v73, v91, v91
	v_max_f32_e32 v89, 0, v73
	v_max_f32_e32 v73, v92, v92
	v_max_f32_e32 v90, 0, v73
	v_max_f32_e32 v73, v93, v93
	v_max_f32_e32 v91, 0, v73
	v_max_f32_e32 v73, v74, v74
	v_max_f32_e32 v74, 0, v73
	v_max_f32_e32 v73, v75, v75
	v_max_f32_e32 v75, 0, v73
	v_max_f32_e32 v73, v76, v76
	v_max_f32_e32 v76, 0, v73
	v_max_f32_e32 v73, v77, v77
	v_max_f32_e32 v66, v66, v66
	v_max_f32_e32 v67, v67, v67
	v_max_f32_e32 v68, v68, v68
	v_max_f32_e32 v69, v69, v69
	v_max_f32_e32 v77, 0, v73
	v_max_f32_e32 v66, 0, v66
	v_max_f32_e32 v67, 0, v67
	v_max_f32_e32 v68, 0, v68
	v_max_f32_e32 v69, 0, v69
	v_pk_mul_f32 v[74:75], v[74:75], v[74:75]
	v_pk_mul_f32 v[76:77], v[76:77], v[76:77]
	v_pk_mul_f32 v[66:67], v[66:67], v[66:67]
	v_pk_mul_f32 v[68:69], v[68:69], v[68:69]
	v_cvt_pk_bf16_f32 v74, v74, v75
	v_cvt_pk_bf16_f32 v75, v76, v77
	v_lshl_add_u64 v[76:77], v[80:81], 0, v[86:87]
	v_cvt_pk_bf16_f32 v66, v66, v67
	v_cvt_pk_bf16_f32 v67, v68, v69
	v_lshl_add_u64 v[68:69], v[82:83], 0, v[86:87]
	v_lshlrev_b64 v[76:77], 6, v[76:77]
	v_lshlrev_b64 v[68:69], 6, v[68:69]
	v_pk_mul_f32 v[88:89], v[88:89], v[88:89]
	v_pk_mul_f32 v[90:91], v[90:91], v[90:91]
	v_lshl_add_u64 v[76:77], s[30:31], 0, v[76:77]
	v_lshl_add_u64 v[68:69], s[30:31], 0, v[68:69]
	v_cvt_pk_bf16_f32 v88, v88, v89
	v_cvt_pk_bf16_f32 v89, v90, v91
	v_lshl_add_u64 v[76:77], v[76:77], 0, v[70:71]
	v_lshl_add_u64 v[68:69], v[68:69], 0, v[84:85]
	v_max_f32_e32 v62, v62, v62
	v_max_f32_e32 v63, v63, v63
	v_max_f32_e32 v64, v64, v64
	v_max_f32_e32 v65, v65, v65
	v_max_f32_e32 v54, v54, v54
	v_max_f32_e32 v55, v55, v55
	v_max_f32_e32 v56, v56, v56
	v_max_f32_e32 v57, v57, v57
	v_max_f32_e32 v50, v50, v50
	v_max_f32_e32 v51, v51, v51
	v_max_f32_e32 v52, v52, v52
	v_max_f32_e32 v53, v53, v53
	global_store_dwordx2 v[94:95], v[88:89], off offset:32
	global_store_dwordx2 v[76:77], v[74:75], off
	global_store_dwordx2 v[68:69], v[66:67], off
	v_or_b32_e32 v66, 64, v72
	v_max_f32_e32 v62, 0, v62
	v_max_f32_e32 v63, 0, v63
	v_max_f32_e32 v64, 0, v64
	v_max_f32_e32 v65, 0, v65
	v_max_f32_e32 v54, 0, v54
	v_max_f32_e32 v55, 0, v55
	v_max_f32_e32 v56, 0, v56
	v_max_f32_e32 v57, 0, v57
	v_max_f32_e32 v50, 0, v50
	v_max_f32_e32 v51, 0, v51
	v_max_f32_e32 v52, 0, v52
	v_max_f32_e32 v53, 0, v53
	v_ashrrev_i32_e32 v67, 31, v66
	v_pk_mul_f32 v[62:63], v[62:63], v[62:63]
	v_pk_mul_f32 v[64:65], v[64:65], v[64:65]
	v_pk_mul_f32 v[54:55], v[54:55], v[54:55]
	v_pk_mul_f32 v[56:57], v[56:57], v[56:57]
	v_pk_mul_f32 v[50:51], v[50:51], v[50:51]
	v_pk_mul_f32 v[52:53], v[52:53], v[52:53]
	v_cvt_pk_bf16_f32 v62, v62, v63
	v_cvt_pk_bf16_f32 v63, v64, v65
	v_lshl_add_u64 v[64:65], v[78:79], 0, v[66:67]
	v_max_f32_e32 v58, v58, v58
	v_max_f32_e32 v59, v59, v59
	v_max_f32_e32 v60, v60, v60
	v_max_f32_e32 v61, v61, v61
	v_cvt_pk_bf16_f32 v54, v54, v55
	v_cvt_pk_bf16_f32 v55, v56, v57
	v_lshl_add_u64 v[56:57], v[80:81], 0, v[66:67]
	v_cvt_pk_bf16_f32 v50, v50, v51
	v_cvt_pk_bf16_f32 v51, v52, v53
	v_lshl_add_u64 v[52:53], v[82:83], 0, v[66:67]
	v_lshlrev_b64 v[64:65], 6, v[64:65]
	v_max_f32_e32 v58, 0, v58
	v_max_f32_e32 v59, 0, v59
	v_max_f32_e32 v60, 0, v60
	v_max_f32_e32 v61, 0, v61
	v_lshlrev_b64 v[56:57], 6, v[56:57]
	v_lshlrev_b64 v[52:53], 6, v[52:53]
	v_lshl_add_u64 v[64:65], s[30:31], 0, v[64:65]
	v_pk_mul_f32 v[58:59], v[58:59], v[58:59]
	v_pk_mul_f32 v[60:61], v[60:61], v[60:61]
	v_lshl_add_u64 v[56:57], s[30:31], 0, v[56:57]
	v_lshl_add_u64 v[52:53], s[30:31], 0, v[52:53]
	v_lshl_add_u64 v[64:65], v[64:65], 0, v[70:71]
	v_cvt_pk_bf16_f32 v58, v58, v59
	v_cvt_pk_bf16_f32 v59, v60, v61
	v_lshl_add_u64 v[56:57], v[56:57], 0, v[70:71]
	v_lshl_add_u64 v[52:53], v[52:53], 0, v[84:85]
	v_max_f32_e32 v46, v46, v46
	v_max_f32_e32 v47, v47, v47
	v_max_f32_e32 v48, v48, v48
	v_max_f32_e32 v49, v49, v49
	v_max_f32_e32 v38, v38, v38
	v_max_f32_e32 v39, v39, v39
	v_max_f32_e32 v40, v40, v40
	v_max_f32_e32 v41, v41, v41
	v_max_f32_e32 v34, v34, v34
	v_max_f32_e32 v35, v35, v35
	v_max_f32_e32 v36, v36, v36
	v_max_f32_e32 v37, v37, v37
	global_store_dwordx2 v[64:65], v[62:63], off
	global_store_dwordx2 v[64:65], v[58:59], off offset:32
	global_store_dwordx2 v[56:57], v[54:55], off
	global_store_dwordx2 v[52:53], v[50:51], off
	v_or_b32_e32 v50, 0x50, v72
	v_max_f32_e32 v46, 0, v46
	v_max_f32_e32 v47, 0, v47
	v_max_f32_e32 v48, 0, v48
	v_max_f32_e32 v49, 0, v49
	v_max_f32_e32 v38, 0, v38
	v_max_f32_e32 v39, 0, v39
	v_max_f32_e32 v40, 0, v40
	v_max_f32_e32 v41, 0, v41
	v_max_f32_e32 v34, 0, v34
	v_max_f32_e32 v35, 0, v35
	v_max_f32_e32 v36, 0, v36
	v_max_f32_e32 v37, 0, v37
	v_ashrrev_i32_e32 v51, 31, v50
	v_pk_mul_f32 v[46:47], v[46:47], v[46:47]
	v_pk_mul_f32 v[48:49], v[48:49], v[48:49]
	v_pk_mul_f32 v[38:39], v[38:39], v[38:39]
	v_pk_mul_f32 v[40:41], v[40:41], v[40:41]
	v_pk_mul_f32 v[34:35], v[34:35], v[34:35]
	v_pk_mul_f32 v[36:37], v[36:37], v[36:37]
	v_cvt_pk_bf16_f32 v46, v46, v47
	v_cvt_pk_bf16_f32 v47, v48, v49
	v_lshl_add_u64 v[48:49], v[78:79], 0, v[50:51]
	v_max_f32_e32 v42, v42, v42
	v_max_f32_e32 v43, v43, v43
	v_max_f32_e32 v44, v44, v44
	v_max_f32_e32 v45, v45, v45
	v_cvt_pk_bf16_f32 v38, v38, v39
	v_cvt_pk_bf16_f32 v39, v40, v41
	v_lshl_add_u64 v[40:41], v[80:81], 0, v[50:51]
	v_cvt_pk_bf16_f32 v34, v34, v35
	v_cvt_pk_bf16_f32 v35, v36, v37
	v_lshl_add_u64 v[36:37], v[82:83], 0, v[50:51]
	v_lshlrev_b64 v[48:49], 6, v[48:49]
	v_max_f32_e32 v42, 0, v42
	v_max_f32_e32 v43, 0, v43
	v_max_f32_e32 v44, 0, v44
	v_max_f32_e32 v45, 0, v45
	v_lshlrev_b64 v[40:41], 6, v[40:41]
	v_lshlrev_b64 v[36:37], 6, v[36:37]
	v_lshl_add_u64 v[48:49], s[30:31], 0, v[48:49]
	v_pk_mul_f32 v[42:43], v[42:43], v[42:43]
	v_pk_mul_f32 v[44:45], v[44:45], v[44:45]
	v_lshl_add_u64 v[40:41], s[30:31], 0, v[40:41]
	v_lshl_add_u64 v[36:37], s[30:31], 0, v[36:37]
	v_lshl_add_u64 v[48:49], v[48:49], 0, v[70:71]
	v_cvt_pk_bf16_f32 v42, v42, v43
	v_cvt_pk_bf16_f32 v43, v44, v45
	v_lshl_add_u64 v[40:41], v[40:41], 0, v[70:71]
	v_lshl_add_u64 v[36:37], v[36:37], 0, v[84:85]
	v_max_f32_e32 v30, v30, v30
	v_max_f32_e32 v31, v31, v31
	v_max_f32_e32 v32, v32, v32
	v_max_f32_e32 v33, v33, v33
	v_max_f32_e32 v12, v12, v12
	v_max_f32_e32 v13, v13, v13
	v_max_f32_e32 v14, v14, v14
	v_max_f32_e32 v15, v15, v15
	v_max_f32_e32 v4, v4, v4
	v_max_f32_e32 v5, v5, v5
	v_max_f32_e32 v6, v6, v6
	v_max_f32_e32 v7, v7, v7
	global_store_dwordx2 v[48:49], v[46:47], off
	global_store_dwordx2 v[48:49], v[42:43], off offset:32
	global_store_dwordx2 v[40:41], v[38:39], off
	global_store_dwordx2 v[36:37], v[34:35], off
	v_or_b32_e32 v34, 0x60, v72
	v_max_f32_e32 v30, 0, v30
	v_max_f32_e32 v31, 0, v31
	v_max_f32_e32 v32, 0, v32
	v_max_f32_e32 v33, 0, v33
	v_max_f32_e32 v12, 0, v12
	v_max_f32_e32 v13, 0, v13
	v_max_f32_e32 v14, 0, v14
	v_max_f32_e32 v15, 0, v15
	v_max_f32_e32 v4, 0, v4
	v_max_f32_e32 v5, 0, v5
	v_max_f32_e32 v6, 0, v6
	v_max_f32_e32 v7, 0, v7
	v_ashrrev_i32_e32 v35, 31, v34
	v_pk_mul_f32 v[30:31], v[30:31], v[30:31]
	v_pk_mul_f32 v[32:33], v[32:33], v[32:33]
	v_pk_mul_f32 v[12:13], v[12:13], v[12:13]
	v_pk_mul_f32 v[14:15], v[14:15], v[14:15]
	v_pk_mul_f32 v[4:5], v[4:5], v[4:5]
	v_pk_mul_f32 v[6:7], v[6:7], v[6:7]
	v_cvt_pk_bf16_f32 v30, v30, v31
	v_cvt_pk_bf16_f32 v31, v32, v33
	v_lshl_add_u64 v[32:33], v[78:79], 0, v[34:35]
	v_max_f32_e32 v18, v18, v18
	v_max_f32_e32 v19, v19, v19
	v_max_f32_e32 v20, v20, v20
	v_max_f32_e32 v21, v21, v21
	v_cvt_pk_bf16_f32 v12, v12, v13
	v_cvt_pk_bf16_f32 v13, v14, v15
	v_lshl_add_u64 v[14:15], v[80:81], 0, v[34:35]
	v_cvt_pk_bf16_f32 v4, v4, v5
	v_cvt_pk_bf16_f32 v5, v6, v7
	v_lshl_add_u64 v[6:7], v[82:83], 0, v[34:35]
	v_lshlrev_b64 v[32:33], 6, v[32:33]
	v_max_f32_e32 v18, 0, v18
	v_max_f32_e32 v19, 0, v19
	v_max_f32_e32 v20, 0, v20
	v_max_f32_e32 v21, 0, v21
	v_lshlrev_b64 v[14:15], 6, v[14:15]
	v_lshlrev_b64 v[6:7], 6, v[6:7]
	v_lshl_add_u64 v[32:33], s[30:31], 0, v[32:33]
	v_pk_mul_f32 v[18:19], v[18:19], v[18:19]
	v_pk_mul_f32 v[20:21], v[20:21], v[20:21]
	v_lshl_add_u64 v[14:15], s[30:31], 0, v[14:15]
	v_lshl_add_u64 v[6:7], s[30:31], 0, v[6:7]
	v_lshl_add_u64 v[32:33], v[32:33], 0, v[70:71]
	v_cvt_pk_bf16_f32 v18, v18, v19
	v_cvt_pk_bf16_f32 v19, v20, v21
	v_lshl_add_u64 v[14:15], v[14:15], 0, v[70:71]
	v_lshl_add_u64 v[6:7], v[6:7], 0, v[84:85]
	v_max_f32_e32 v0, v0, v0
	v_max_f32_e32 v1, v1, v1
	v_max_f32_e32 v2, v2, v2
	v_max_f32_e32 v3, v3, v3
	global_store_dwordx2 v[32:33], v[30:31], off
	global_store_dwordx2 v[32:33], v[18:19], off offset:32
	global_store_dwordx2 v[14:15], v[12:13], off
	global_store_dwordx2 v[6:7], v[4:5], off
	v_or_b32_e32 v4, 0x70, v72
	v_max_f32_e32 v0, 0, v0
	v_max_f32_e32 v1, 0, v1
	v_max_f32_e32 v2, 0, v2
	v_max_f32_e32 v3, 0, v3
	v_ashrrev_i32_e32 v5, 31, v4
	v_pk_mul_f32 v[0:1], v[0:1], v[0:1]
	v_pk_mul_f32 v[2:3], v[2:3], v[2:3]
	v_cvt_pk_bf16_f32 v0, v0, v1
	v_cvt_pk_bf16_f32 v1, v2, v3
	v_lshl_add_u64 v[2:3], v[78:79], 0, v[4:5]
	v_lshlrev_b64 v[2:3], 6, v[2:3]
	v_lshl_add_u64 v[2:3], s[30:31], 0, v[2:3]
	v_lshl_add_u64 v[2:3], v[2:3], 0, v[70:71]
	global_store_dwordx2 v[2:3], v[0:1], off
	v_max_f32_e32 v0, v26, v26
	v_max_f32_e32 v1, v27, v27
	v_max_f32_e32 v6, v28, v28
	v_max_f32_e32 v7, v29, v29
	v_max_f32_e32 v0, 0, v0
	v_max_f32_e32 v1, 0, v1
	v_max_f32_e32 v6, 0, v6
	v_max_f32_e32 v7, 0, v7
	v_pk_mul_f32 v[0:1], v[0:1], v[0:1]
	v_pk_mul_f32 v[6:7], v[6:7], v[6:7]
	v_cvt_pk_bf16_f32 v0, v0, v1
	v_cvt_pk_bf16_f32 v1, v6, v7
	global_store_dwordx2 v[2:3], v[0:1], off offset:32
	v_max_f32_e32 v0, v22, v22
	v_max_f32_e32 v1, v23, v23
	v_max_f32_e32 v2, v24, v24
	v_max_f32_e32 v3, v25, v25
	v_max_f32_e32 v0, 0, v0
	v_max_f32_e32 v1, 0, v1
	v_max_f32_e32 v2, 0, v2
	v_max_f32_e32 v3, 0, v3
	v_pk_mul_f32 v[0:1], v[0:1], v[0:1]
	v_pk_mul_f32 v[2:3], v[2:3], v[2:3]
	v_cvt_pk_bf16_f32 v0, v0, v1
	v_cvt_pk_bf16_f32 v1, v2, v3
	v_lshl_add_u64 v[2:3], v[80:81], 0, v[4:5]
	v_lshlrev_b64 v[2:3], 6, v[2:3]
	v_lshl_add_u64 v[2:3], s[30:31], 0, v[2:3]
	v_lshl_add_u64 v[2:3], v[2:3], 0, v[70:71]
	global_store_dwordx2 v[2:3], v[0:1], off
	v_max_f32_e32 v0, v8, v8
	v_max_f32_e32 v1, v9, v9
	v_max_f32_e32 v2, v10, v10
	v_max_f32_e32 v3, v11, v11
	v_max_f32_e32 v0, 0, v0
	v_max_f32_e32 v1, 0, v1
	v_max_f32_e32 v2, 0, v2
	v_max_f32_e32 v3, 0, v3
	v_pk_mul_f32 v[0:1], v[0:1], v[0:1]
	v_pk_mul_f32 v[2:3], v[2:3], v[2:3]
	v_cvt_pk_bf16_f32 v0, v0, v1
	v_cvt_pk_bf16_f32 v1, v2, v3
	v_lshl_add_u64 v[2:3], v[82:83], 0, v[4:5]
	v_lshlrev_b64 v[2:3], 6, v[2:3]
	v_lshl_add_u64 v[2:3], s[30:31], 0, v[2:3]
	v_lshl_add_u64 v[2:3], v[2:3], 0, v[84:85]
	global_store_dwordx2 v[2:3], v[0:1], off

.LBB0_1146:
	v_cmp_gt_i32_e32 vcc, 8, v199
	s_or_b64 s[46:47], s[46:47], exec
	s_and_saveexec_b64 s[48:49], vcc
	s_cbranch_execz .LBB0_1145
	s_cmp_eq_u32 s99, 1
	s_cbranch_scc0 .Lpf_none_m1
	s_mov_b32 s99, 0
	s_waitcnt vmcnt(0)
	v_mov_b32_e32 v1, v248
	s_branch .Lpf_have_m1
.Lpf_none_m1:
	v_lshl_add_u64 v[2:3], v[16:17], 2, s[0:1]
	global_atomic_add v1, v[2:3], v229, off sc0
.Lpf_have_m1:
	s_movk_i32 s34, 0x120
	s_waitcnt vmcnt(0)
	v_cmp_gt_i32_e32 vcc, s34, v1
	s_and_saveexec_b64 s[50:51], vcc
	s_xor_b64 s[50:51], exec, s[50:51]
	s_cbranch_execz .LBB0_1149
	v_ashrrev_i32_e32 v0, 31, v1
	v_lshrrev_b32_e32 v0, 30, v0
	v_add_u32_e32 v4, v1, v0
	v_lshrrev_b32_e32 v2, 2, v16
	v_lshrrev_b32_e32 v0, 2, v4
	s_movk_i32 s34, 0x48
	v_mad_u64_u32 v[2:3], s[52:53], v2, s34, v[0:1]
	v_lshlrev_b32_e32 v0, 2, v16
	v_and_b32_e32 v3, -4, v4
	v_and_b32_e32 v0, 12, v0
	v_sub_u32_e32 v1, v1, v3
	v_add_u32_e32 v0, v1, v0
	v_lshl_or_b32 v0, v2, 6, v0

.LBB0_1155:
	s_lshl_b32 s44, s46, 15
	v_mfma_f32_16x16x32_bf16 v[158:161], v[70:73], v[130:133], v[158:161]
	v_add_u32_e32 v162, s44, v240
	s_mov_b64 s[40:41], -1
	s_cmp_gt_u32 s49, 28
	v_mfma_f32_16x16x32_bf16 v[154:157], v[78:81], v[130:133], v[154:157]
	v_mfma_f32_16x16x32_bf16 v[150:153], v[82:85], v[130:133], v[150:153]
	v_mfma_f32_16x16x32_bf16 v[146:149], v[86:89], v[130:133], v[146:149]
	ds_read_b128 v[130:133], v162 offset:4096
	v_mfma_f32_16x16x32_bf16 v[142:145], v[70:73], v[126:129], v[142:145]
	v_mfma_f32_16x16x32_bf16 v[138:141], v[78:81], v[126:129], v[138:141]
	v_mfma_f32_16x16x32_bf16 v[134:137], v[82:85], v[126:129], v[134:137]
	v_mfma_f32_16x16x32_bf16 v[114:117], v[86:89], v[126:129], v[114:117]
	ds_read_b128 v[126:129], v162 offset:5120
	v_mfma_f32_16x16x32_bf16 v[110:113], v[70:73], v[122:125], v[110:113]
	v_mfma_f32_16x16x32_bf16 v[106:109], v[78:81], v[122:125], v[106:109]
	v_mfma_f32_16x16x32_bf16 v[102:105], v[82:85], v[122:125], v[102:105]
	v_mfma_f32_16x16x32_bf16 v[98:101], v[86:89], v[122:125], v[98:101]
	ds_read_b128 v[122:125], v162 offset:6144
	ds_read_b128 v[174:177], v162 offset:7168
	v_mfma_f32_16x16x32_bf16 v[94:97], v[70:73], v[118:121], v[94:97]
	s_waitcnt lgkmcnt(0)
	v_mfma_f32_16x16x32_bf16 v[90:93], v[78:81], v[118:121], v[90:93]
	v_mfma_f32_16x16x32_bf16 v[74:77], v[82:85], v[118:121], v[74:77]
	v_mfma_f32_16x16x32_bf16 v[66:69], v[86:89], v[118:121], v[66:69]
	s_cbranch_scc1 .Lvw_m1a
	s_waitcnt vmcnt(8)

.Ldma_m1a_3:
	v_mfma_f32_16x16x32_bf16 v[38:41], v[82:85], v[126:129], v[38:41]
	v_mfma_f32_16x16x32_bf16 v[34:37], v[86:89], v[126:129], v[34:37]
	ds_read_b128 v[126:129], v202 offset:1024
	v_mfma_f32_16x16x32_bf16 v[30:33], v[70:73], v[122:125], v[30:33]
	v_mfma_f32_16x16x32_bf16 v[18:21], v[78:81], v[122:125], v[18:21]
	v_mfma_f32_16x16x32_bf16 v[12:15], v[82:85], v[122:125], v[12:15]
	v_mfma_f32_16x16x32_bf16 v[4:7], v[86:89], v[122:125], v[4:7]
	ds_read_b128 v[122:125], v202 offset:2048
	ds_read_b128 v[118:121], v202 offset:3072
	s_nop 0
	ds_read_b128 v[190:193], v202 offset:4096
	ds_read_b128 v[186:189], v202 offset:5120
	ds_read_b128 v[182:185], v202 offset:6144
	v_mfma_f32_16x16x32_bf16 v[0:3], v[70:73], v[174:177], v[0:3]
	v_mfma_f32_16x16x32_bf16 v[26:29], v[78:81], v[174:177], v[26:29]
	v_mfma_f32_16x16x32_bf16 v[22:25], v[82:85], v[174:177], v[22:25]
	v_mfma_f32_16x16x32_bf16 v[8:11], v[86:89], v[174:177], v[8:11]
	ds_read_b128 v[174:177], v202 offset:7168
	s_nop 0
	s_waitcnt lgkmcnt(4)
	v_mfma_f32_16x16x32_bf16 v[158:161], v[178:181], v[130:133], v[158:161]
	v_mfma_f32_16x16x32_bf16 v[154:157], v[170:173], v[130:133], v[154:157]
	v_mfma_f32_16x16x32_bf16 v[150:153], v[166:169], v[130:133], v[150:153]
	v_mfma_f32_16x16x32_bf16 v[146:149], v[162:165], v[130:133], v[146:149]
	v_mfma_f32_16x16x32_bf16 v[142:145], v[178:181], v[126:129], v[142:145]
	v_mfma_f32_16x16x32_bf16 v[138:141], v[170:173], v[126:129], v[138:141]
	v_mfma_f32_16x16x32_bf16 v[134:137], v[166:169], v[126:129], v[134:137]
	v_mfma_f32_16x16x32_bf16 v[114:117], v[162:165], v[126:129], v[114:117]
	v_mfma_f32_16x16x32_bf16 v[110:113], v[178:181], v[122:125], v[110:113]
	v_mfma_f32_16x16x32_bf16 v[106:109], v[170:173], v[122:125], v[106:109]
	v_mfma_f32_16x16x32_bf16 v[102:105], v[166:169], v[122:125], v[102:105]
	v_mfma_f32_16x16x32_bf16 v[98:101], v[162:165], v[122:125], v[98:101]
	v_mfma_f32_16x16x32_bf16 v[94:97], v[178:181], v[118:121], v[94:97]
	v_mfma_f32_16x16x32_bf16 v[90:93], v[170:173], v[118:121], v[90:93]
	v_mfma_f32_16x16x32_bf16 v[74:77], v[166:169], v[118:121], v[74:77]
	v_mfma_f32_16x16x32_bf16 v[66:69], v[162:165], v[118:121], v[66:69]
	s_cbranch_vccnz .LBB0_1170
	s_cmp_lt_u32 s48, 2
	s_cbranch_scc1 .Lvw_m1b
	s_waitcnt vmcnt(8)

.Lvw_m1b:
	s_cmp_lg_u32 s48, 1
	s_cbranch_scc0 .Lvw_m1b4
	s_waitcnt vmcnt(0)
	s_branch .LBB0_1170

.LBB0_1241:
	s_waitcnt lgkmcnt(0)
	s_getreg_b32 s0, hwreg(HW_REG_XCC_ID, 0, 4)
	s_and_b32 s34, s0, 7
	s_add_i32 s0, s42, 32
	s_ashr_i32 s1, s0, 31
	s_lshl_b64 s[0:1], s[0:1], 2
	v_readlane_b32 s40, v252, 55
	v_readlane_b32 s41, v252, 56
	s_add_u32 s0, s40, s0
	s_addc_u32 s1, s41, s1
	v_mov_b32_e32 v124, 0
	v_mov_b32_e32 v16, s34
	s_mov_b32 s99, 0
	s_branch .LBB0_1243

.Lpfa_skip_m2:
	s_mov_b32 s99, 1
	v_or_b32_e32 v0, s43, v127
	v_and_b32_e32 v1, 64, v126
	v_add_u32_e32 v0, v0, v128
	v_lshlrev_b32_e32 v2, 2, v125
	v_or3_b32 v6, v2, v1, s34
	v_ashrrev_i32_e32 v1, 31, v0
	v_lshlrev_b64 v[2:3], 11, v[0:1]
	v_lshl_add_u64 v[2:3], s[6:7], 0, v[2:3]
	v_lshlrev_b32_e32 v6, 1, v6
	v_mov_b32_e32 v7, v17
	v_cvt_pk_bf16_f32 v4, v86, v87
	v_cvt_pk_bf16_f32 v5, v88, v89
	v_lshl_add_u64 v[2:3], v[2:3], 0, v[6:7]
	global_store_dwordx2 v[2:3], v[4:5], off
	v_cvt_pk_bf16_f32 v4, v82, v83
	v_cvt_pk_bf16_f32 v5, v84, v85
	global_store_dwordx2 v[2:3], v[4:5], off offset:32
	v_cvt_pk_bf16_f32 v4, v74, v75
	v_cvt_pk_bf16_f32 v5, v76, v77
	global_store_dwordx2 v[2:3], v[4:5], off offset:64
	v_cvt_pk_bf16_f32 v4, v66, v67
	v_cvt_pk_bf16_f32 v5, v68, v69
	global_store_dwordx2 v[2:3], v[4:5], off offset:96
	v_or_b32_e32 v2, 16, v0
	v_ashrrev_i32_e32 v3, 31, v2
	v_lshlrev_b64 v[2:3], 11, v[2:3]
	v_lshl_add_u64 v[2:3], s[6:7], 0, v[2:3]
	v_cvt_pk_bf16_f32 v4, v54, v55
	v_cvt_pk_bf16_f32 v5, v56, v57
	v_lshl_add_u64 v[2:3], v[2:3], 0, v[6:7]
	global_store_dwordx2 v[2:3], v[4:5], off
	v_cvt_pk_bf16_f32 v4, v46, v47
	v_cvt_pk_bf16_f32 v5, v48, v49
	global_store_dwordx2 v[2:3], v[4:5], off offset:32
	v_cvt_pk_bf16_f32 v4, v38, v39
	v_cvt_pk_bf16_f32 v5, v40, v41
	global_store_dwordx2 v[2:3], v[4:5], off offset:64
	v_cvt_pk_bf16_f32 v4, v34, v35
	v_cvt_pk_bf16_f32 v5, v36, v37
	global_store_dwordx2 v[2:3], v[4:5], off offset:96
	v_or_b32_e32 v2, 32, v0
	v_ashrrev_i32_e32 v3, 31, v2
	v_lshlrev_b64 v[2:3], 11, v[2:3]
	v_lshl_add_u64 v[2:3], s[6:7], 0, v[2:3]
	v_cvt_pk_bf16_f32 v4, v70, v71
	v_cvt_pk_bf16_f32 v5, v72, v73
	v_lshl_add_u64 v[2:3], v[2:3], 0, v[6:7]
	v_or_b32_e32 v0, 48, v0
	global_store_dwordx2 v[2:3], v[4:5], off
	v_cvt_pk_bf16_f32 v4, v62, v63
	v_cvt_pk_bf16_f32 v5, v64, v65
	v_ashrrev_i32_e32 v1, 31, v0
	global_store_dwordx2 v[2:3], v[4:5], off offset:32
	v_cvt_pk_bf16_f32 v4, v50, v51
	v_cvt_pk_bf16_f32 v5, v52, v53
	v_lshlrev_b64 v[0:1], 11, v[0:1]
	global_store_dwordx2 v[2:3], v[4:5], off offset:64
	v_cvt_pk_bf16_f32 v4, v42, v43
	v_cvt_pk_bf16_f32 v5, v44, v45
	v_lshl_add_u64 v[0:1], s[6:7], 0, v[0:1]
	global_store_dwordx2 v[2:3], v[4:5], off offset:96
	v_cvt_pk_bf16_f32 v2, v26, v27
	v_cvt_pk_bf16_f32 v3, v28, v29
	v_lshl_add_u64 v[0:1], v[0:1], 0, v[6:7]
	global_store_dwordx2 v[0:1], v[2:3], off
	v_cvt_pk_bf16_f32 v2, v30, v31
	v_cvt_pk_bf16_f32 v3, v32, v33
	global_store_dwordx2 v[0:1], v[2:3], off offset:32
	v_cvt_pk_bf16_f32 v2, v78, v79
	v_cvt_pk_bf16_f32 v3, v80, v81
	global_store_dwordx2 v[0:1], v[2:3], off offset:64
	v_cvt_pk_bf16_f32 v2, v58, v59
	v_cvt_pk_bf16_f32 v3, v60, v61
	global_store_dwordx2 v[0:1], v[2:3], off offset:96

.LBB0_1247:
	v_cmp_gt_i32_e32 vcc, 8, v124
	s_or_b64 s[46:47], s[46:47], exec
	s_and_saveexec_b64 s[48:49], vcc
	s_cbranch_execz .LBB0_1246
	s_cmp_eq_u32 s99, 1
	s_cbranch_scc0 .Lpf_none_m2
	s_mov_b32 s99, 0
	s_waitcnt vmcnt(0)
	v_mov_b32_e32 v1, v248
	s_branch .Lpf_have_m2

.Lpf_have_m2:
	s_movk_i32 s34, 0x90
	s_waitcnt vmcnt(0)
	v_cmp_gt_i32_e32 vcc, s34, v1
	s_and_saveexec_b64 s[50:51], vcc
	s_xor_b64 s[50:51], exec, s[50:51]
	s_cbranch_execz .LBB0_1250
	v_lshrrev_b32_e32 v0, 31, v1
	v_add_u32_e32 v4, v1, v0
	v_lshrrev_b32_e32 v2, 2, v16
	v_lshrrev_b32_e32 v0, 1, v4
	s_movk_i32 s34, 0x48
	v_mad_u64_u32 v[2:3], s[52:53], v2, s34, v[0:1]
	v_lshlrev_b32_e32 v0, 1, v16
	v_and_b32_e32 v3, -2, v4
	v_and_b32_e32 v0, 6, v0
	v_sub_u32_e32 v1, v1, v3
	v_add_u32_e32 v0, v1, v0
	v_lshl_or_b32 v0, v2, 6, v0

.LBB0_1256:
	s_mul_i32 s44, s46, 0x6000
	v_mfma_f32_16x16x32_bf16 v[86:89], v[0:3], v[22:25], v[86:89]
	v_add_u32_e32 v90, s44, v129
	s_mov_b64 s[40:41], -1
	s_cmpk_gt_u32 s53, 0x7a
	v_mfma_f32_16x16x32_bf16 v[82:85], v[4:7], v[22:25], v[82:85]
	v_mfma_f32_16x16x32_bf16 v[74:77], v[8:11], v[22:25], v[74:77]
	v_mfma_f32_16x16x32_bf16 v[66:69], v[12:15], v[22:25], v[66:69]
	ds_read_b128 v[22:25], v90 offset:2048
	ds_read_b128 v[98:101], v90 offset:3072
	v_mfma_f32_16x16x32_bf16 v[54:57], v[0:3], v[18:21], v[54:57]
	s_waitcnt lgkmcnt(0)
	v_mfma_f32_16x16x32_bf16 v[46:49], v[4:7], v[18:21], v[46:49]
	v_mfma_f32_16x16x32_bf16 v[38:41], v[8:11], v[18:21], v[38:41]
	v_mfma_f32_16x16x32_bf16 v[34:37], v[12:15], v[18:21], v[34:37]
	s_cbranch_scc1 .Lvw_m2a
	s_waitcnt vmcnt(12)

.Lvw_m2a:
	s_cmp_lg_u32 s52, 1
	s_cbranch_scc0 .Lvw_m2a6
	s_waitcnt vmcnt(0)
	s_branch .LBB0_1264
.Lvw_m2a6:
	s_waitcnt vmcnt(6)
	s_branch .LBB0_1264
